# P4/P5 tail transposes run only on blocks whose CU-mate is not a small-tile block (blocks 128..255 and 384..511), so the critical small tiles have their CU alone
# speedup vs baseline: 1.0098x; 1.0087x over previous
.LBB0_658:
	s_cmp_lt_u32 s2, 0x80
	s_cbranch_scc1 .Ltb_done
	s_sub_u32 s19, s2, 0x80
	s_cmp_lt_u32 s19, 0x80
	s_cbranch_scc1 .Ltb_ok
	s_cmp_lt_u32 s19, 0x100
	s_cbranch_scc1 .Ltb_done
	s_sub_u32 s19, s19, 0x80
.Ltb_ok:
	s_load_dwordx2 s[30:31], s[0:1], 0x40
	s_load_dwordx2 s[32:33], s[0:1], 0xb0
	s_load_dwordx2 s[34:35], s[0:1], 0xc8
	s_load_dwordx2 s[36:37], s[0:1], 0xd0
	s_load_dwordx2 s[38:39], s[0:1], 0xe0
	s_movk_i32 s3, 256
	v_lshrrev_b32_e32 v0, 4, v204
	v_and_b32_e32 v1, 15, v204
	v_lshlrev_b32_e32 v1, 4, v1
	v_lshrrev_b32_e32 v2, 3, v204
	v_and_b32_e32 v3, 7, v204
	v_add_u32_e32 v8, 0, v0
	v_mul_u32_u24_e32 v8, 0x104, v8
	v_add3_u32 v8, v8, v1, 32
	v_add_u32_e32 v72, 0x4100, v8
	v_add_u32_e32 v9, 16, v0
	v_mul_u32_u24_e32 v9, 0x104, v9
	v_add3_u32 v9, v9, v1, 32
	v_add_u32_e32 v73, 0x4100, v9
	v_add_u32_e32 v10, 32, v0
	v_mul_u32_u24_e32 v10, 0x104, v10
	v_add3_u32 v10, v10, v1, 32
	v_add_u32_e32 v74, 0x4100, v10
	v_add_u32_e32 v11, 48, v0
	v_mul_u32_u24_e32 v11, 0x104, v11
	v_add3_u32 v11, v11, v1, 32
	v_add_u32_e32 v75, 0x4100, v11
	v_mul_u32_u24_e32 v12, 0x820, v3
	v_lshl_add_u32 v12, v2, 2, v12
	v_add_u32_e32 v12, 32, v12
	v_add_u32_e32 v13, 0x410, v12
	v_add_u32_e32 v76, 0x4100, v12
	v_add_u32_e32 v77, 0x4100, v13
	v_lshlrev_b32_e32 v14, 12, v2
	v_lshl_add_u32 v14, v3, 4, v14
	v_add_u32_e32 v78, 0, v0
	v_add_u32_e32 v79, 16, v0
	v_add_u32_e32 v80, 32, v0
	v_add_u32_e32 v81, 48, v0
	s_waitcnt lgkmcnt(0)
	s_mov_b32 s4, s19
	s_add_u32 s4, s4, 0x1b00
	s_cmpk_ge_u32 s4, 0x1f00
	s_cbranch_scc1 .Ltb_done
	s_mov_b32 s5, s4

.Ltc_ok:
	s_load_dwordx2 s[30:31], s[0:1], 0x40
	s_load_dwordx2 s[32:33], s[0:1], 0xb0
	s_load_dwordx2 s[34:35], s[0:1], 0xc8
	s_load_dwordx2 s[36:37], s[0:1], 0xd0
	s_load_dwordx2 s[38:39], s[0:1], 0xe0
	s_movk_i32 s3, 256
	v_lshrrev_b32_e32 v0, 4, v204
	v_and_b32_e32 v1, 15, v204
	v_lshlrev_b32_e32 v1, 4, v1
	v_lshrrev_b32_e32 v2, 3, v204
	v_and_b32_e32 v3, 7, v204
	v_add_u32_e32 v8, 0, v0
	v_mul_u32_u24_e32 v8, 0x104, v8
	v_add3_u32 v8, v8, v1, 32
	v_add_u32_e32 v72, 0x4100, v8
	v_add_u32_e32 v9, 16, v0
	v_mul_u32_u24_e32 v9, 0x104, v9
	v_add3_u32 v9, v9, v1, 32
	v_add_u32_e32 v73, 0x4100, v9
	v_add_u32_e32 v10, 32, v0
	v_mul_u32_u24_e32 v10, 0x104, v10
	v_add3_u32 v10, v10, v1, 32
	v_add_u32_e32 v74, 0x4100, v10
	v_add_u32_e32 v11, 48, v0
	v_mul_u32_u24_e32 v11, 0x104, v11
	v_add3_u32 v11, v11, v1, 32
	v_add_u32_e32 v75, 0x4100, v11
	v_mul_u32_u24_e32 v12, 0x820, v3
	v_lshl_add_u32 v12, v2, 2, v12
	v_add_u32_e32 v12, 32, v12
	v_add_u32_e32 v13, 0x410, v12
	v_add_u32_e32 v76, 0x4100, v12
	v_add_u32_e32 v77, 0x4100, v13
	v_lshlrev_b32_e32 v14, 12, v2
	v_lshl_add_u32 v14, v3, 4, v14
	v_add_u32_e32 v78, 0, v0
	v_add_u32_e32 v79, 16, v0
	v_add_u32_e32 v80, 32, v0
	v_add_u32_e32 v81, 48, v0
	s_waitcnt lgkmcnt(0)
	s_mov_b32 s4, s19
	s_add_u32 s4, s4, 0x1f00
	s_cmpk_ge_u32 s4, 0x2300
	s_cbranch_scc1 .Ltc_done
	s_mov_b32 s5, s4
